# RWKV scan pair: two grouped LDS waits instead of three
# baseline (speedup 1.0000x reference)
.LBB0_652:
	ds_read_b128 v[20:23], v6 offset:0
	ds_read_b128 v[24:27], v6 offset:256
	ds_read_b128 v[56:59], v7 offset:0
	ds_read_b128 v[28:31], v6 offset:512
	ds_read_b128 v[32:35], v6 offset:768
	ds_read_b128 v[36:39], v6 offset:1024
	ds_read_b128 v[40:43], v6 offset:1280
	ds_read_b128 v[48:51], v6 offset:1792
	ds_read_b128 v[44:47], v6 offset:1536
	ds_read_b128 v[52:55], v6 offset:2048
	s_waitcnt lgkmcnt(9)
	v_pk_mul_f32 v[10:11], v[2:3], v[20:21] op_sel_hi:[0,1]
	ds_read_b128 v[68:71], v6 offset:2304
	s_waitcnt lgkmcnt(8)
	v_pk_fma_f32 v[14:15], v[2:3], v[24:25], v[58:59] op_sel_hi:[0,1,1]
	v_pk_fma_f32 v[10:11], v[2:3], v[22:23], v[10:11] op_sel:[1,0,0] op_sel_hi:[1,1,1]
	ds_read_b128 v[72:75], v6 offset:2560
	v_pk_fma_f32 v[14:15], v[2:3], v[26:27], v[14:15] op_sel:[1,0,0] op_sel_hi:[1,1,1]
	s_waitcnt lgkmcnt(8)
	v_pk_fma_f32 v[10:11], v[4:5], v[28:29], v[10:11] op_sel_hi:[0,1,1]
	s_waitcnt lgkmcnt(7)
	v_pk_fma_f32 v[14:15], v[4:5], v[32:33], v[14:15] op_sel_hi:[0,1,1]
	ds_read_b128 v[104:107], v7 offset:256
	v_pk_fma_f32 v[10:11], v[4:5], v[30:31], v[10:11] op_sel:[1,0,0] op_sel_hi:[1,1,1]
	s_waitcnt lgkmcnt(7)
	v_pk_mul_f32 v[114:115], v[2:3], v[36:37]
	ds_read_b128 v[76:79], v6 offset:2816
	v_pk_mul_f32 v[116:117], v[4:5], v[38:39]
	v_add_f32_dpp v10, v10, v10 row_ror:8 row_mask:0xf bank_mask:0xf bound_ctrl:1
	v_add_f32_dpp v11, v11, v11 row_ror:8 row_mask:0xf bank_mask:0xf bound_ctrl:1
	ds_read_b128 v[80:83], v6 offset:3072
	v_pk_fma_f32 v[14:15], v[4:5], v[34:35], v[14:15] op_sel:[1,0,0] op_sel_hi:[1,1,1]
	v_add_f32_dpp v10, v10, v10 row_ror:4 row_mask:0xf bank_mask:0xf bound_ctrl:1
	ds_read_b128 v[84:87], v6 offset:3328
	v_add_f32_dpp v11, v11, v11 row_ror:4 row_mask:0xf bank_mask:0xf bound_ctrl:1
	s_waitcnt lgkmcnt(9)
	v_pk_fma_f32 v[114:115], v[40:41], v[56:57], v[114:115] op_sel_hi:[1,0,1]
	v_add_f32_dpp v10, v10, v10 row_ror:2 row_mask:0xf bank_mask:0xf bound_ctrl:1
	ds_read_b128 v[88:91], v6 offset:3584
	v_add_f32_dpp v11, v11, v11 row_ror:2 row_mask:0xf bank_mask:0xf bound_ctrl:1
	v_pk_fma_f32 v[116:117], v[42:43], v[56:57], v[116:117] op_sel_hi:[1,0,1]
	ds_read_b128 v[96:99], v6 offset:4096
	v_add_f32_dpp v10, v10, v10 row_ror:1 row_mask:0xf bank_mask:0xf bound_ctrl:1
	v_add_f32_dpp v11, v11, v11 row_ror:1 row_mask:0xf bank_mask:0xf bound_ctrl:1
	s_waitcnt lgkmcnt(10)
	v_pk_fma_f32 v[114:115], v[48:49], v[56:57], v[114:115] op_sel:[0,1,0] op_sel_hi:[1,1,1]
	ds_read_b128 v[92:95], v6 offset:3840
	v_pk_fma_f32 v[116:117], v[50:51], v[56:57], v[116:117] op_sel:[0,1,0] op_sel_hi:[1,1,1]
	s_waitcnt lgkmcnt(10)
	v_pk_fma_f32 v[114:115], v[44:45], v[10:11], v[114:115] op_sel_hi:[1,0,1] neg_lo:[1,0,0] neg_hi:[1,0,0]
	ds_read_b128 v[100:103], v6 offset:4352
	v_pk_fma_f32 v[116:117], v[46:47], v[10:11], v[116:117] op_sel_hi:[1,0,1] neg_lo:[1,0,0] neg_hi:[1,0,0]
	s_waitcnt lgkmcnt(10)
	v_pk_fma_f32 v[2:3], v[52:53], v[10:11], v[114:115] op_sel:[0,1,0] op_sel_hi:[1,1,1] neg_lo:[1,0,0] neg_hi:[1,0,0]
	v_pk_fma_f32 v[4:5], v[54:55], v[10:11], v[116:117] op_sel:[0,1,0] op_sel_hi:[1,1,1] neg_lo:[1,0,0] neg_hi:[1,0,0]
	ds_write2st64_b32 v9, v14, v15 offset0:0 offset1:4
	s_waitcnt lgkmcnt(4)
	v_pk_mul_f32 v[10:11], v[2:3], v[68:69] op_sel_hi:[0,1]
	ds_read_b128 v[20:23], v6 offset:4608
	v_pk_fma_f32 v[14:15], v[2:3], v[72:73], v[106:107] op_sel_hi:[0,1,1]
	v_pk_fma_f32 v[10:11], v[2:3], v[70:71], v[10:11] op_sel:[1,0,0] op_sel_hi:[1,1,1]
	ds_read_b128 v[24:27], v6 offset:4864
	v_pk_fma_f32 v[14:15], v[2:3], v[74:75], v[14:15] op_sel:[1,0,0] op_sel_hi:[1,1,1]
	v_pk_fma_f32 v[10:11], v[4:5], v[76:77], v[10:11] op_sel_hi:[0,1,1]
	v_pk_fma_f32 v[14:15], v[4:5], v[80:81], v[14:15] op_sel_hi:[0,1,1]
	ds_read_b128 v[56:59], v7 offset:512
	v_pk_fma_f32 v[10:11], v[4:5], v[78:79], v[10:11] op_sel:[1,0,0] op_sel_hi:[1,1,1]
	v_pk_mul_f32 v[114:115], v[2:3], v[84:85]
	ds_read_b128 v[28:31], v6 offset:5120
	v_pk_mul_f32 v[116:117], v[4:5], v[86:87]
	v_add_f32_dpp v10, v10, v10 row_ror:8 row_mask:0xf bank_mask:0xf bound_ctrl:1
	v_add_f32_dpp v11, v11, v11 row_ror:8 row_mask:0xf bank_mask:0xf bound_ctrl:1
	ds_read_b128 v[32:35], v6 offset:5376
	v_pk_fma_f32 v[14:15], v[4:5], v[82:83], v[14:15] op_sel:[1,0,0] op_sel_hi:[1,1,1]
	v_add_f32_dpp v10, v10, v10 row_ror:4 row_mask:0xf bank_mask:0xf bound_ctrl:1
	ds_read_b128 v[36:39], v6 offset:5632
	v_add_f32_dpp v11, v11, v11 row_ror:4 row_mask:0xf bank_mask:0xf bound_ctrl:1
	v_pk_fma_f32 v[114:115], v[88:89], v[104:105], v[114:115] op_sel_hi:[1,0,1]
	v_add_f32_dpp v10, v10, v10 row_ror:2 row_mask:0xf bank_mask:0xf bound_ctrl:1
	ds_read_b128 v[40:43], v6 offset:5888
	v_add_f32_dpp v11, v11, v11 row_ror:2 row_mask:0xf bank_mask:0xf bound_ctrl:1
	v_pk_fma_f32 v[116:117], v[90:91], v[104:105], v[116:117] op_sel_hi:[1,0,1]
	ds_read_b128 v[48:51], v6 offset:6400
	v_add_f32_dpp v10, v10, v10 row_ror:1 row_mask:0xf bank_mask:0xf bound_ctrl:1
	v_add_f32_dpp v11, v11, v11 row_ror:1 row_mask:0xf bank_mask:0xf bound_ctrl:1
	s_waitcnt lgkmcnt(9)
	v_pk_fma_f32 v[114:115], v[96:97], v[104:105], v[114:115] op_sel:[0,1,0] op_sel_hi:[1,1,1]
	ds_read_b128 v[44:47], v6 offset:6144
	v_pk_fma_f32 v[116:117], v[98:99], v[104:105], v[116:117] op_sel:[0,1,0] op_sel_hi:[1,1,1]
	v_pk_fma_f32 v[114:115], v[92:93], v[10:11], v[114:115] op_sel_hi:[1,0,1] neg_lo:[1,0,0] neg_hi:[1,0,0]
	ds_read_b128 v[52:55], v6 offset:6656
	v_pk_fma_f32 v[116:117], v[94:95], v[10:11], v[116:117] op_sel_hi:[1,0,1] neg_lo:[1,0,0] neg_hi:[1,0,0]
	v_pk_fma_f32 v[2:3], v[100:101], v[10:11], v[114:115] op_sel:[0,1,0] op_sel_hi:[1,1,1] neg_lo:[1,0,0] neg_hi:[1,0,0]
	v_pk_fma_f32 v[4:5], v[102:103], v[10:11], v[116:117] op_sel:[0,1,0] op_sel_hi:[1,1,1] neg_lo:[1,0,0] neg_hi:[1,0,0]
	ds_write2st64_b32 v9, v14, v15 offset0:8 offset1:12
	s_waitcnt lgkmcnt(4)
	v_pk_mul_f32 v[10:11], v[2:3], v[20:21] op_sel_hi:[0,1]
	ds_read_b128 v[68:71], v6 offset:6912
	v_pk_fma_f32 v[14:15], v[2:3], v[24:25], v[58:59] op_sel_hi:[0,1,1]
	v_pk_fma_f32 v[10:11], v[2:3], v[22:23], v[10:11] op_sel:[1,0,0] op_sel_hi:[1,1,1]
	ds_read_b128 v[72:75], v6 offset:7168
	v_pk_fma_f32 v[14:15], v[2:3], v[26:27], v[14:15] op_sel:[1,0,0] op_sel_hi:[1,1,1]
	v_pk_fma_f32 v[10:11], v[4:5], v[28:29], v[10:11] op_sel_hi:[0,1,1]
	v_pk_fma_f32 v[14:15], v[4:5], v[32:33], v[14:15] op_sel_hi:[0,1,1]
	ds_read_b128 v[104:107], v7 offset:768
	v_pk_fma_f32 v[10:11], v[4:5], v[30:31], v[10:11] op_sel:[1,0,0] op_sel_hi:[1,1,1]
	v_pk_mul_f32 v[114:115], v[2:3], v[36:37]
	ds_read_b128 v[76:79], v6 offset:7424
	v_pk_mul_f32 v[116:117], v[4:5], v[38:39]
	v_add_f32_dpp v10, v10, v10 row_ror:8 row_mask:0xf bank_mask:0xf bound_ctrl:1
	v_add_f32_dpp v11, v11, v11 row_ror:8 row_mask:0xf bank_mask:0xf bound_ctrl:1
	ds_read_b128 v[80:83], v6 offset:7680
	v_pk_fma_f32 v[14:15], v[4:5], v[34:35], v[14:15] op_sel:[1,0,0] op_sel_hi:[1,1,1]
	v_add_f32_dpp v10, v10, v10 row_ror:4 row_mask:0xf bank_mask:0xf bound_ctrl:1
	ds_read_b128 v[84:87], v6 offset:7936
	v_add_f32_dpp v11, v11, v11 row_ror:4 row_mask:0xf bank_mask:0xf bound_ctrl:1
	v_pk_fma_f32 v[114:115], v[40:41], v[56:57], v[114:115] op_sel_hi:[1,0,1]
	v_add_f32_dpp v10, v10, v10 row_ror:2 row_mask:0xf bank_mask:0xf bound_ctrl:1
	ds_read_b128 v[88:91], v6 offset:8192
	v_add_f32_dpp v11, v11, v11 row_ror:2 row_mask:0xf bank_mask:0xf bound_ctrl:1
	v_pk_fma_f32 v[116:117], v[42:43], v[56:57], v[116:117] op_sel_hi:[1,0,1]
	ds_read_b128 v[96:99], v6 offset:8704
	v_add_f32_dpp v10, v10, v10 row_ror:1 row_mask:0xf bank_mask:0xf bound_ctrl:1
	v_add_f32_dpp v11, v11, v11 row_ror:1 row_mask:0xf bank_mask:0xf bound_ctrl:1
	s_waitcnt lgkmcnt(9)
	v_pk_fma_f32 v[114:115], v[48:49], v[56:57], v[114:115] op_sel:[0,1,0] op_sel_hi:[1,1,1]
	ds_read_b128 v[92:95], v6 offset:8448
	v_pk_fma_f32 v[116:117], v[50:51], v[56:57], v[116:117] op_sel:[0,1,0] op_sel_hi:[1,1,1]
	v_pk_fma_f32 v[114:115], v[44:45], v[10:11], v[114:115] op_sel_hi:[1,0,1] neg_lo:[1,0,0] neg_hi:[1,0,0]
	ds_read_b128 v[100:103], v6 offset:8960
	v_pk_fma_f32 v[116:117], v[46:47], v[10:11], v[116:117] op_sel_hi:[1,0,1] neg_lo:[1,0,0] neg_hi:[1,0,0]
	v_pk_fma_f32 v[2:3], v[52:53], v[10:11], v[114:115] op_sel:[0,1,0] op_sel_hi:[1,1,1] neg_lo:[1,0,0] neg_hi:[1,0,0]
	v_pk_fma_f32 v[4:5], v[54:55], v[10:11], v[116:117] op_sel:[0,1,0] op_sel_hi:[1,1,1] neg_lo:[1,0,0] neg_hi:[1,0,0]
	ds_write2st64_b32 v9, v14, v15 offset0:16 offset1:20
	s_waitcnt lgkmcnt(4)
	v_pk_mul_f32 v[10:11], v[2:3], v[68:69] op_sel_hi:[0,1]
	ds_read_b128 v[20:23], v6 offset:9216
	v_pk_fma_f32 v[14:15], v[2:3], v[72:73], v[106:107] op_sel_hi:[0,1,1]
	v_pk_fma_f32 v[10:11], v[2:3], v[70:71], v[10:11] op_sel:[1,0,0] op_sel_hi:[1,1,1]
	ds_read_b128 v[24:27], v6 offset:9472
	v_pk_fma_f32 v[14:15], v[2:3], v[74:75], v[14:15] op_sel:[1,0,0] op_sel_hi:[1,1,1]
	v_pk_fma_f32 v[10:11], v[4:5], v[76:77], v[10:11] op_sel_hi:[0,1,1]
	v_pk_fma_f32 v[14:15], v[4:5], v[80:81], v[14:15] op_sel_hi:[0,1,1]
	ds_read_b128 v[56:59], v7 offset:1024
	v_pk_fma_f32 v[10:11], v[4:5], v[78:79], v[10:11] op_sel:[1,0,0] op_sel_hi:[1,1,1]
	v_pk_mul_f32 v[114:115], v[2:3], v[84:85]
	ds_read_b128 v[28:31], v6 offset:9728
	v_pk_mul_f32 v[116:117], v[4:5], v[86:87]
	v_add_f32_dpp v10, v10, v10 row_ror:8 row_mask:0xf bank_mask:0xf bound_ctrl:1
	v_add_f32_dpp v11, v11, v11 row_ror:8 row_mask:0xf bank_mask:0xf bound_ctrl:1
	ds_read_b128 v[32:35], v6 offset:9984
	v_pk_fma_f32 v[14:15], v[4:5], v[82:83], v[14:15] op_sel:[1,0,0] op_sel_hi:[1,1,1]
	v_add_f32_dpp v10, v10, v10 row_ror:4 row_mask:0xf bank_mask:0xf bound_ctrl:1
	ds_read_b128 v[36:39], v6 offset:10240
	v_add_f32_dpp v11, v11, v11 row_ror:4 row_mask:0xf bank_mask:0xf bound_ctrl:1
	v_pk_fma_f32 v[114:115], v[88:89], v[104:105], v[114:115] op_sel_hi:[1,0,1]
	v_add_f32_dpp v10, v10, v10 row_ror:2 row_mask:0xf bank_mask:0xf bound_ctrl:1
	ds_read_b128 v[40:43], v6 offset:10496
	v_add_f32_dpp v11, v11, v11 row_ror:2 row_mask:0xf bank_mask:0xf bound_ctrl:1
	v_pk_fma_f32 v[116:117], v[90:91], v[104:105], v[116:117] op_sel_hi:[1,0,1]
	ds_read_b128 v[48:51], v6 offset:11008
	v_add_f32_dpp v10, v10, v10 row_ror:1 row_mask:0xf bank_mask:0xf bound_ctrl:1
	v_add_f32_dpp v11, v11, v11 row_ror:1 row_mask:0xf bank_mask:0xf bound_ctrl:1
	s_waitcnt lgkmcnt(9)
	v_pk_fma_f32 v[114:115], v[96:97], v[104:105], v[114:115] op_sel:[0,1,0] op_sel_hi:[1,1,1]
	ds_read_b128 v[44:47], v6 offset:10752
	v_pk_fma_f32 v[116:117], v[98:99], v[104:105], v[116:117] op_sel:[0,1,0] op_sel_hi:[1,1,1]
	v_pk_fma_f32 v[114:115], v[92:93], v[10:11], v[114:115] op_sel_hi:[1,0,1] neg_lo:[1,0,0] neg_hi:[1,0,0]
	ds_read_b128 v[52:55], v6 offset:11264
	v_pk_fma_f32 v[116:117], v[94:95], v[10:11], v[116:117] op_sel_hi:[1,0,1] neg_lo:[1,0,0] neg_hi:[1,0,0]
	v_pk_fma_f32 v[2:3], v[100:101], v[10:11], v[114:115] op_sel:[0,1,0] op_sel_hi:[1,1,1] neg_lo:[1,0,0] neg_hi:[1,0,0]
	v_pk_fma_f32 v[4:5], v[102:103], v[10:11], v[116:117] op_sel:[0,1,0] op_sel_hi:[1,1,1] neg_lo:[1,0,0] neg_hi:[1,0,0]
	ds_write2st64_b32 v9, v14, v15 offset0:24 offset1:28
	s_waitcnt lgkmcnt(4)
	v_pk_mul_f32 v[10:11], v[2:3], v[20:21] op_sel_hi:[0,1]
	ds_read_b128 v[68:71], v6 offset:11520
	v_pk_fma_f32 v[14:15], v[2:3], v[24:25], v[58:59] op_sel_hi:[0,1,1]
	v_pk_fma_f32 v[10:11], v[2:3], v[22:23], v[10:11] op_sel:[1,0,0] op_sel_hi:[1,1,1]
	ds_read_b128 v[72:75], v6 offset:11776
	v_pk_fma_f32 v[14:15], v[2:3], v[26:27], v[14:15] op_sel:[1,0,0] op_sel_hi:[1,1,1]
	v_pk_fma_f32 v[10:11], v[4:5], v[28:29], v[10:11] op_sel_hi:[0,1,1]
	v_pk_fma_f32 v[14:15], v[4:5], v[32:33], v[14:15] op_sel_hi:[0,1,1]
	ds_read_b128 v[104:107], v7 offset:1280
	v_pk_fma_f32 v[10:11], v[4:5], v[30:31], v[10:11] op_sel:[1,0,0] op_sel_hi:[1,1,1]
	v_pk_mul_f32 v[114:115], v[2:3], v[36:37]
	ds_read_b128 v[76:79], v6 offset:12032
	v_pk_mul_f32 v[116:117], v[4:5], v[38:39]
	v_add_f32_dpp v10, v10, v10 row_ror:8 row_mask:0xf bank_mask:0xf bound_ctrl:1
	v_add_f32_dpp v11, v11, v11 row_ror:8 row_mask:0xf bank_mask:0xf bound_ctrl:1
	ds_read_b128 v[80:83], v6 offset:12288
	v_pk_fma_f32 v[14:15], v[4:5], v[34:35], v[14:15] op_sel:[1,0,0] op_sel_hi:[1,1,1]
	v_add_f32_dpp v10, v10, v10 row_ror:4 row_mask:0xf bank_mask:0xf bound_ctrl:1
	ds_read_b128 v[84:87], v6 offset:12544
	v_add_f32_dpp v11, v11, v11 row_ror:4 row_mask:0xf bank_mask:0xf bound_ctrl:1
	v_pk_fma_f32 v[114:115], v[40:41], v[56:57], v[114:115] op_sel_hi:[1,0,1]
	v_add_f32_dpp v10, v10, v10 row_ror:2 row_mask:0xf bank_mask:0xf bound_ctrl:1
	ds_read_b128 v[88:91], v6 offset:12800
	v_add_f32_dpp v11, v11, v11 row_ror:2 row_mask:0xf bank_mask:0xf bound_ctrl:1
	v_pk_fma_f32 v[116:117], v[42:43], v[56:57], v[116:117] op_sel_hi:[1,0,1]
	ds_read_b128 v[96:99], v6 offset:13312
	v_add_f32_dpp v10, v10, v10 row_ror:1 row_mask:0xf bank_mask:0xf bound_ctrl:1
	v_add_f32_dpp v11, v11, v11 row_ror:1 row_mask:0xf bank_mask:0xf bound_ctrl:1
	s_waitcnt lgkmcnt(9)
	v_pk_fma_f32 v[114:115], v[48:49], v[56:57], v[114:115] op_sel:[0,1,0] op_sel_hi:[1,1,1]
	ds_read_b128 v[92:95], v6 offset:13056
	v_pk_fma_f32 v[116:117], v[50:51], v[56:57], v[116:117] op_sel:[0,1,0] op_sel_hi:[1,1,1]
	v_pk_fma_f32 v[114:115], v[44:45], v[10:11], v[114:115] op_sel_hi:[1,0,1] neg_lo:[1,0,0] neg_hi:[1,0,0]
	ds_read_b128 v[100:103], v6 offset:13568
	v_pk_fma_f32 v[116:117], v[46:47], v[10:11], v[116:117] op_sel_hi:[1,0,1] neg_lo:[1,0,0] neg_hi:[1,0,0]
	v_pk_fma_f32 v[2:3], v[52:53], v[10:11], v[114:115] op_sel:[0,1,0] op_sel_hi:[1,1,1] neg_lo:[1,0,0] neg_hi:[1,0,0]
	v_pk_fma_f32 v[4:5], v[54:55], v[10:11], v[116:117] op_sel:[0,1,0] op_sel_hi:[1,1,1] neg_lo:[1,0,0] neg_hi:[1,0,0]
	ds_write2st64_b32 v9, v14, v15 offset0:32 offset1:36
	s_waitcnt lgkmcnt(4)
	v_pk_mul_f32 v[10:11], v[2:3], v[68:69] op_sel_hi:[0,1]
	ds_read_b128 v[20:23], v6 offset:13824
	v_pk_fma_f32 v[14:15], v[2:3], v[72:73], v[106:107] op_sel_hi:[0,1,1]
	v_pk_fma_f32 v[10:11], v[2:3], v[70:71], v[10:11] op_sel:[1,0,0] op_sel_hi:[1,1,1]
	ds_read_b128 v[24:27], v6 offset:14080
	v_pk_fma_f32 v[14:15], v[2:3], v[74:75], v[14:15] op_sel:[1,0,0] op_sel_hi:[1,1,1]
	v_pk_fma_f32 v[10:11], v[4:5], v[76:77], v[10:11] op_sel_hi:[0,1,1]
	v_pk_fma_f32 v[14:15], v[4:5], v[80:81], v[14:15] op_sel_hi:[0,1,1]
	ds_read_b128 v[56:59], v7 offset:1536
	v_pk_fma_f32 v[10:11], v[4:5], v[78:79], v[10:11] op_sel:[1,0,0] op_sel_hi:[1,1,1]
	v_pk_mul_f32 v[114:115], v[2:3], v[84:85]
	ds_read_b128 v[28:31], v6 offset:14336
	v_pk_mul_f32 v[116:117], v[4:5], v[86:87]
	v_add_f32_dpp v10, v10, v10 row_ror:8 row_mask:0xf bank_mask:0xf bound_ctrl:1
	v_add_f32_dpp v11, v11, v11 row_ror:8 row_mask:0xf bank_mask:0xf bound_ctrl:1
	ds_read_b128 v[32:35], v6 offset:14592
	v_pk_fma_f32 v[14:15], v[4:5], v[82:83], v[14:15] op_sel:[1,0,0] op_sel_hi:[1,1,1]
	v_add_f32_dpp v10, v10, v10 row_ror:4 row_mask:0xf bank_mask:0xf bound_ctrl:1
	ds_read_b128 v[36:39], v6 offset:14848
	v_add_f32_dpp v11, v11, v11 row_ror:4 row_mask:0xf bank_mask:0xf bound_ctrl:1
	v_pk_fma_f32 v[114:115], v[88:89], v[104:105], v[114:115] op_sel_hi:[1,0,1]
	v_add_f32_dpp v10, v10, v10 row_ror:2 row_mask:0xf bank_mask:0xf bound_ctrl:1
	ds_read_b128 v[40:43], v6 offset:15104
	v_add_f32_dpp v11, v11, v11 row_ror:2 row_mask:0xf bank_mask:0xf bound_ctrl:1
	v_pk_fma_f32 v[116:117], v[90:91], v[104:105], v[116:117] op_sel_hi:[1,0,1]
	ds_read_b128 v[48:51], v6 offset:15616
	v_add_f32_dpp v10, v10, v10 row_ror:1 row_mask:0xf bank_mask:0xf bound_ctrl:1
	v_add_f32_dpp v11, v11, v11 row_ror:1 row_mask:0xf bank_mask:0xf bound_ctrl:1
	s_waitcnt lgkmcnt(9)
	v_pk_fma_f32 v[114:115], v[96:97], v[104:105], v[114:115] op_sel:[0,1,0] op_sel_hi:[1,1,1]
	ds_read_b128 v[44:47], v6 offset:15360
	v_pk_fma_f32 v[116:117], v[98:99], v[104:105], v[116:117] op_sel:[0,1,0] op_sel_hi:[1,1,1]
	v_pk_fma_f32 v[114:115], v[92:93], v[10:11], v[114:115] op_sel_hi:[1,0,1] neg_lo:[1,0,0] neg_hi:[1,0,0]
	ds_read_b128 v[52:55], v6 offset:15872
	v_pk_fma_f32 v[116:117], v[94:95], v[10:11], v[116:117] op_sel_hi:[1,0,1] neg_lo:[1,0,0] neg_hi:[1,0,0]
	v_pk_fma_f32 v[2:3], v[100:101], v[10:11], v[114:115] op_sel:[0,1,0] op_sel_hi:[1,1,1] neg_lo:[1,0,0] neg_hi:[1,0,0]
	v_pk_fma_f32 v[4:5], v[102:103], v[10:11], v[116:117] op_sel:[0,1,0] op_sel_hi:[1,1,1] neg_lo:[1,0,0] neg_hi:[1,0,0]
	ds_write2st64_b32 v9, v14, v15 offset0:40 offset1:44
	s_waitcnt lgkmcnt(4)
	v_pk_mul_f32 v[10:11], v[2:3], v[20:21] op_sel_hi:[0,1]
	ds_read_b128 v[68:71], v6 offset:16128
	v_pk_fma_f32 v[14:15], v[2:3], v[24:25], v[58:59] op_sel_hi:[0,1,1]
	v_pk_fma_f32 v[10:11], v[2:3], v[22:23], v[10:11] op_sel:[1,0,0] op_sel_hi:[1,1,1]
	ds_read_b128 v[72:75], v6 offset:16384
	v_pk_fma_f32 v[14:15], v[2:3], v[26:27], v[14:15] op_sel:[1,0,0] op_sel_hi:[1,1,1]
	v_pk_fma_f32 v[10:11], v[4:5], v[28:29], v[10:11] op_sel_hi:[0,1,1]
	v_pk_fma_f32 v[14:15], v[4:5], v[32:33], v[14:15] op_sel_hi:[0,1,1]
	ds_read_b128 v[104:107], v7 offset:1792
	v_pk_fma_f32 v[10:11], v[4:5], v[30:31], v[10:11] op_sel:[1,0,0] op_sel_hi:[1,1,1]
	v_pk_mul_f32 v[114:115], v[2:3], v[36:37]
	ds_read_b128 v[76:79], v6 offset:16640
	v_pk_mul_f32 v[116:117], v[4:5], v[38:39]
	v_add_f32_dpp v10, v10, v10 row_ror:8 row_mask:0xf bank_mask:0xf bound_ctrl:1
	v_add_f32_dpp v11, v11, v11 row_ror:8 row_mask:0xf bank_mask:0xf bound_ctrl:1
	ds_read_b128 v[80:83], v6 offset:16896
	v_pk_fma_f32 v[14:15], v[4:5], v[34:35], v[14:15] op_sel:[1,0,0] op_sel_hi:[1,1,1]
	v_add_f32_dpp v10, v10, v10 row_ror:4 row_mask:0xf bank_mask:0xf bound_ctrl:1
	ds_read_b128 v[84:87], v6 offset:17152
	v_add_f32_dpp v11, v11, v11 row_ror:4 row_mask:0xf bank_mask:0xf bound_ctrl:1
	v_pk_fma_f32 v[114:115], v[40:41], v[56:57], v[114:115] op_sel_hi:[1,0,1]
	v_add_f32_dpp v10, v10, v10 row_ror:2 row_mask:0xf bank_mask:0xf bound_ctrl:1
	ds_read_b128 v[88:91], v6 offset:17408
	v_add_f32_dpp v11, v11, v11 row_ror:2 row_mask:0xf bank_mask:0xf bound_ctrl:1
	v_pk_fma_f32 v[116:117], v[42:43], v[56:57], v[116:117] op_sel_hi:[1,0,1]
	ds_read_b128 v[96:99], v6 offset:17920
	v_add_f32_dpp v10, v10, v10 row_ror:1 row_mask:0xf bank_mask:0xf bound_ctrl:1
	v_add_f32_dpp v11, v11, v11 row_ror:1 row_mask:0xf bank_mask:0xf bound_ctrl:1
	s_waitcnt lgkmcnt(9)
	v_pk_fma_f32 v[114:115], v[48:49], v[56:57], v[114:115] op_sel:[0,1,0] op_sel_hi:[1,1,1]
	ds_read_b128 v[92:95], v6 offset:17664
	v_pk_fma_f32 v[116:117], v[50:51], v[56:57], v[116:117] op_sel:[0,1,0] op_sel_hi:[1,1,1]
	v_pk_fma_f32 v[114:115], v[44:45], v[10:11], v[114:115] op_sel_hi:[1,0,1] neg_lo:[1,0,0] neg_hi:[1,0,0]
	ds_read_b128 v[100:103], v6 offset:18176
	v_pk_fma_f32 v[116:117], v[46:47], v[10:11], v[116:117] op_sel_hi:[1,0,1] neg_lo:[1,0,0] neg_hi:[1,0,0]
	v_pk_fma_f32 v[2:3], v[52:53], v[10:11], v[114:115] op_sel:[0,1,0] op_sel_hi:[1,1,1] neg_lo:[1,0,0] neg_hi:[1,0,0]
	v_pk_fma_f32 v[4:5], v[54:55], v[10:11], v[116:117] op_sel:[0,1,0] op_sel_hi:[1,1,1] neg_lo:[1,0,0] neg_hi:[1,0,0]
	ds_write2st64_b32 v9, v14, v15 offset0:48 offset1:52
	s_waitcnt lgkmcnt(4)
	v_pk_mul_f32 v[10:11], v[2:3], v[68:69] op_sel_hi:[0,1]
	ds_read_b128 v[20:23], v6 offset:18432
	v_pk_fma_f32 v[14:15], v[2:3], v[72:73], v[106:107] op_sel_hi:[0,1,1]
	v_pk_fma_f32 v[10:11], v[2:3], v[70:71], v[10:11] op_sel:[1,0,0] op_sel_hi:[1,1,1]
	ds_read_b128 v[24:27], v6 offset:18688
	v_pk_fma_f32 v[14:15], v[2:3], v[74:75], v[14:15] op_sel:[1,0,0] op_sel_hi:[1,1,1]
	v_pk_fma_f32 v[10:11], v[4:5], v[76:77], v[10:11] op_sel_hi:[0,1,1]
	v_pk_fma_f32 v[14:15], v[4:5], v[80:81], v[14:15] op_sel_hi:[0,1,1]
	ds_read_b128 v[56:59], v7 offset:2048
	v_pk_fma_f32 v[10:11], v[4:5], v[78:79], v[10:11] op_sel:[1,0,0] op_sel_hi:[1,1,1]
	v_pk_mul_f32 v[114:115], v[2:3], v[84:85]
	ds_read_b128 v[28:31], v6 offset:18944
	v_pk_mul_f32 v[116:117], v[4:5], v[86:87]
	v_add_f32_dpp v10, v10, v10 row_ror:8 row_mask:0xf bank_mask:0xf bound_ctrl:1
	v_add_f32_dpp v11, v11, v11 row_ror:8 row_mask:0xf bank_mask:0xf bound_ctrl:1
	ds_read_b128 v[32:35], v6 offset:19200
	v_pk_fma_f32 v[14:15], v[4:5], v[82:83], v[14:15] op_sel:[1,0,0] op_sel_hi:[1,1,1]
	v_add_f32_dpp v10, v10, v10 row_ror:4 row_mask:0xf bank_mask:0xf bound_ctrl:1
	ds_read_b128 v[36:39], v6 offset:19456
	v_add_f32_dpp v11, v11, v11 row_ror:4 row_mask:0xf bank_mask:0xf bound_ctrl:1
	v_pk_fma_f32 v[114:115], v[88:89], v[104:105], v[114:115] op_sel_hi:[1,0,1]
	v_add_f32_dpp v10, v10, v10 row_ror:2 row_mask:0xf bank_mask:0xf bound_ctrl:1
	ds_read_b128 v[40:43], v6 offset:19712
	v_add_f32_dpp v11, v11, v11 row_ror:2 row_mask:0xf bank_mask:0xf bound_ctrl:1
	v_pk_fma_f32 v[116:117], v[90:91], v[104:105], v[116:117] op_sel_hi:[1,0,1]
	ds_read_b128 v[48:51], v6 offset:20224
	v_add_f32_dpp v10, v10, v10 row_ror:1 row_mask:0xf bank_mask:0xf bound_ctrl:1
	v_add_f32_dpp v11, v11, v11 row_ror:1 row_mask:0xf bank_mask:0xf bound_ctrl:1
	s_waitcnt lgkmcnt(9)
	v_pk_fma_f32 v[114:115], v[96:97], v[104:105], v[114:115] op_sel:[0,1,0] op_sel_hi:[1,1,1]
	ds_read_b128 v[44:47], v6 offset:19968
	v_pk_fma_f32 v[116:117], v[98:99], v[104:105], v[116:117] op_sel:[0,1,0] op_sel_hi:[1,1,1]
	v_pk_fma_f32 v[114:115], v[92:93], v[10:11], v[114:115] op_sel_hi:[1,0,1] neg_lo:[1,0,0] neg_hi:[1,0,0]
	ds_read_b128 v[52:55], v6 offset:20480
	v_pk_fma_f32 v[116:117], v[94:95], v[10:11], v[116:117] op_sel_hi:[1,0,1] neg_lo:[1,0,0] neg_hi:[1,0,0]
	v_pk_fma_f32 v[2:3], v[100:101], v[10:11], v[114:115] op_sel:[0,1,0] op_sel_hi:[1,1,1] neg_lo:[1,0,0] neg_hi:[1,0,0]
	v_pk_fma_f32 v[4:5], v[102:103], v[10:11], v[116:117] op_sel:[0,1,0] op_sel_hi:[1,1,1] neg_lo:[1,0,0] neg_hi:[1,0,0]
	ds_write2st64_b32 v9, v14, v15 offset0:56 offset1:60
	s_waitcnt lgkmcnt(4)
	v_pk_mul_f32 v[10:11], v[2:3], v[20:21] op_sel_hi:[0,1]
	ds_read_b128 v[68:71], v6 offset:20736
	v_pk_fma_f32 v[14:15], v[2:3], v[24:25], v[58:59] op_sel_hi:[0,1,1]
	v_pk_fma_f32 v[10:11], v[2:3], v[22:23], v[10:11] op_sel:[1,0,0] op_sel_hi:[1,1,1]
	ds_read_b128 v[72:75], v6 offset:20992
	v_pk_fma_f32 v[14:15], v[2:3], v[26:27], v[14:15] op_sel:[1,0,0] op_sel_hi:[1,1,1]
	v_pk_fma_f32 v[10:11], v[4:5], v[28:29], v[10:11] op_sel_hi:[0,1,1]
	v_pk_fma_f32 v[14:15], v[4:5], v[32:33], v[14:15] op_sel_hi:[0,1,1]
	ds_read_b128 v[104:107], v7 offset:2304
	v_pk_fma_f32 v[10:11], v[4:5], v[30:31], v[10:11] op_sel:[1,0,0] op_sel_hi:[1,1,1]
	v_pk_mul_f32 v[114:115], v[2:3], v[36:37]
	ds_read_b128 v[76:79], v6 offset:21248
	v_pk_mul_f32 v[116:117], v[4:5], v[38:39]
	v_add_f32_dpp v10, v10, v10 row_ror:8 row_mask:0xf bank_mask:0xf bound_ctrl:1
	v_add_f32_dpp v11, v11, v11 row_ror:8 row_mask:0xf bank_mask:0xf bound_ctrl:1
	ds_read_b128 v[80:83], v6 offset:21504
	v_pk_fma_f32 v[14:15], v[4:5], v[34:35], v[14:15] op_sel:[1,0,0] op_sel_hi:[1,1,1]
	v_add_f32_dpp v10, v10, v10 row_ror:4 row_mask:0xf bank_mask:0xf bound_ctrl:1
	ds_read_b128 v[84:87], v6 offset:21760
	v_add_f32_dpp v11, v11, v11 row_ror:4 row_mask:0xf bank_mask:0xf bound_ctrl:1
	v_pk_fma_f32 v[114:115], v[40:41], v[56:57], v[114:115] op_sel_hi:[1,0,1]
	v_add_f32_dpp v10, v10, v10 row_ror:2 row_mask:0xf bank_mask:0xf bound_ctrl:1
	ds_read_b128 v[88:91], v6 offset:22016
	v_add_f32_dpp v11, v11, v11 row_ror:2 row_mask:0xf bank_mask:0xf bound_ctrl:1
	v_pk_fma_f32 v[116:117], v[42:43], v[56:57], v[116:117] op_sel_hi:[1,0,1]
	ds_read_b128 v[96:99], v6 offset:22528
	v_add_f32_dpp v10, v10, v10 row_ror:1 row_mask:0xf bank_mask:0xf bound_ctrl:1
	v_add_f32_dpp v11, v11, v11 row_ror:1 row_mask:0xf bank_mask:0xf bound_ctrl:1
	s_waitcnt lgkmcnt(9)
	v_pk_fma_f32 v[114:115], v[48:49], v[56:57], v[114:115] op_sel:[0,1,0] op_sel_hi:[1,1,1]
	ds_read_b128 v[92:95], v6 offset:22272
	v_pk_fma_f32 v[116:117], v[50:51], v[56:57], v[116:117] op_sel:[0,1,0] op_sel_hi:[1,1,1]
	v_pk_fma_f32 v[114:115], v[44:45], v[10:11], v[114:115] op_sel_hi:[1,0,1] neg_lo:[1,0,0] neg_hi:[1,0,0]
	ds_read_b128 v[100:103], v6 offset:22784
	v_pk_fma_f32 v[116:117], v[46:47], v[10:11], v[116:117] op_sel_hi:[1,0,1] neg_lo:[1,0,0] neg_hi:[1,0,0]
	v_pk_fma_f32 v[2:3], v[52:53], v[10:11], v[114:115] op_sel:[0,1,0] op_sel_hi:[1,1,1] neg_lo:[1,0,0] neg_hi:[1,0,0]
	v_pk_fma_f32 v[4:5], v[54:55], v[10:11], v[116:117] op_sel:[0,1,0] op_sel_hi:[1,1,1] neg_lo:[1,0,0] neg_hi:[1,0,0]
	ds_write2st64_b32 v9, v14, v15 offset0:64 offset1:68
	s_waitcnt lgkmcnt(4)
	v_pk_mul_f32 v[10:11], v[2:3], v[68:69] op_sel_hi:[0,1]
	ds_read_b128 v[20:23], v6 offset:23040
	v_pk_fma_f32 v[14:15], v[2:3], v[72:73], v[106:107] op_sel_hi:[0,1,1]
	v_pk_fma_f32 v[10:11], v[2:3], v[70:71], v[10:11] op_sel:[1,0,0] op_sel_hi:[1,1,1]
	ds_read_b128 v[24:27], v6 offset:23296
	v_pk_fma_f32 v[14:15], v[2:3], v[74:75], v[14:15] op_sel:[1,0,0] op_sel_hi:[1,1,1]
	v_pk_fma_f32 v[10:11], v[4:5], v[76:77], v[10:11] op_sel_hi:[0,1,1]
	v_pk_fma_f32 v[14:15], v[4:5], v[80:81], v[14:15] op_sel_hi:[0,1,1]
	ds_read_b128 v[56:59], v7 offset:2560
	v_pk_fma_f32 v[10:11], v[4:5], v[78:79], v[10:11] op_sel:[1,0,0] op_sel_hi:[1,1,1]
	v_pk_mul_f32 v[114:115], v[2:3], v[84:85]
	ds_read_b128 v[28:31], v6 offset:23552
	v_pk_mul_f32 v[116:117], v[4:5], v[86:87]
	v_add_f32_dpp v10, v10, v10 row_ror:8 row_mask:0xf bank_mask:0xf bound_ctrl:1
	v_add_f32_dpp v11, v11, v11 row_ror:8 row_mask:0xf bank_mask:0xf bound_ctrl:1
	ds_read_b128 v[32:35], v6 offset:23808
	v_pk_fma_f32 v[14:15], v[4:5], v[82:83], v[14:15] op_sel:[1,0,0] op_sel_hi:[1,1,1]
	v_add_f32_dpp v10, v10, v10 row_ror:4 row_mask:0xf bank_mask:0xf bound_ctrl:1
	ds_read_b128 v[36:39], v6 offset:24064
	v_add_f32_dpp v11, v11, v11 row_ror:4 row_mask:0xf bank_mask:0xf bound_ctrl:1
	v_pk_fma_f32 v[114:115], v[88:89], v[104:105], v[114:115] op_sel_hi:[1,0,1]
	v_add_f32_dpp v10, v10, v10 row_ror:2 row_mask:0xf bank_mask:0xf bound_ctrl:1
	ds_read_b128 v[40:43], v6 offset:24320
	v_add_f32_dpp v11, v11, v11 row_ror:2 row_mask:0xf bank_mask:0xf bound_ctrl:1
	v_pk_fma_f32 v[116:117], v[90:91], v[104:105], v[116:117] op_sel_hi:[1,0,1]
	ds_read_b128 v[48:51], v6 offset:24832
	v_add_f32_dpp v10, v10, v10 row_ror:1 row_mask:0xf bank_mask:0xf bound_ctrl:1
	v_add_f32_dpp v11, v11, v11 row_ror:1 row_mask:0xf bank_mask:0xf bound_ctrl:1
	s_waitcnt lgkmcnt(9)
	v_pk_fma_f32 v[114:115], v[96:97], v[104:105], v[114:115] op_sel:[0,1,0] op_sel_hi:[1,1,1]
	ds_read_b128 v[44:47], v6 offset:24576
	v_pk_fma_f32 v[116:117], v[98:99], v[104:105], v[116:117] op_sel:[0,1,0] op_sel_hi:[1,1,1]
	v_pk_fma_f32 v[114:115], v[92:93], v[10:11], v[114:115] op_sel_hi:[1,0,1] neg_lo:[1,0,0] neg_hi:[1,0,0]
	ds_read_b128 v[52:55], v6 offset:25088
	v_pk_fma_f32 v[116:117], v[94:95], v[10:11], v[116:117] op_sel_hi:[1,0,1] neg_lo:[1,0,0] neg_hi:[1,0,0]
	v_pk_fma_f32 v[2:3], v[100:101], v[10:11], v[114:115] op_sel:[0,1,0] op_sel_hi:[1,1,1] neg_lo:[1,0,0] neg_hi:[1,0,0]
	v_pk_fma_f32 v[4:5], v[102:103], v[10:11], v[116:117] op_sel:[0,1,0] op_sel_hi:[1,1,1] neg_lo:[1,0,0] neg_hi:[1,0,0]
	ds_write2st64_b32 v9, v14, v15 offset0:72 offset1:76
	s_waitcnt lgkmcnt(4)
	v_pk_mul_f32 v[10:11], v[2:3], v[20:21] op_sel_hi:[0,1]
	ds_read_b128 v[68:71], v6 offset:25344
	v_pk_fma_f32 v[14:15], v[2:3], v[24:25], v[58:59] op_sel_hi:[0,1,1]
	v_pk_fma_f32 v[10:11], v[2:3], v[22:23], v[10:11] op_sel:[1,0,0] op_sel_hi:[1,1,1]
	ds_read_b128 v[72:75], v6 offset:25600
	v_pk_fma_f32 v[14:15], v[2:3], v[26:27], v[14:15] op_sel:[1,0,0] op_sel_hi:[1,1,1]
	v_pk_fma_f32 v[10:11], v[4:5], v[28:29], v[10:11] op_sel_hi:[0,1,1]
	v_pk_fma_f32 v[14:15], v[4:5], v[32:33], v[14:15] op_sel_hi:[0,1,1]
	ds_read_b128 v[104:107], v7 offset:2816
	v_pk_fma_f32 v[10:11], v[4:5], v[30:31], v[10:11] op_sel:[1,0,0] op_sel_hi:[1,1,1]
	v_pk_mul_f32 v[114:115], v[2:3], v[36:37]
	ds_read_b128 v[76:79], v6 offset:25856
	v_pk_mul_f32 v[116:117], v[4:5], v[38:39]
	v_add_f32_dpp v10, v10, v10 row_ror:8 row_mask:0xf bank_mask:0xf bound_ctrl:1
	v_add_f32_dpp v11, v11, v11 row_ror:8 row_mask:0xf bank_mask:0xf bound_ctrl:1
	ds_read_b128 v[80:83], v6 offset:26112
	v_pk_fma_f32 v[14:15], v[4:5], v[34:35], v[14:15] op_sel:[1,0,0] op_sel_hi:[1,1,1]
	v_add_f32_dpp v10, v10, v10 row_ror:4 row_mask:0xf bank_mask:0xf bound_ctrl:1
	ds_read_b128 v[84:87], v6 offset:26368
	v_add_f32_dpp v11, v11, v11 row_ror:4 row_mask:0xf bank_mask:0xf bound_ctrl:1
	v_pk_fma_f32 v[114:115], v[40:41], v[56:57], v[114:115] op_sel_hi:[1,0,1]
	v_add_f32_dpp v10, v10, v10 row_ror:2 row_mask:0xf bank_mask:0xf bound_ctrl:1
	ds_read_b128 v[88:91], v6 offset:26624
	v_add_f32_dpp v11, v11, v11 row_ror:2 row_mask:0xf bank_mask:0xf bound_ctrl:1
	v_pk_fma_f32 v[116:117], v[42:43], v[56:57], v[116:117] op_sel_hi:[1,0,1]
	ds_read_b128 v[96:99], v6 offset:27136
	v_add_f32_dpp v10, v10, v10 row_ror:1 row_mask:0xf bank_mask:0xf bound_ctrl:1
	v_add_f32_dpp v11, v11, v11 row_ror:1 row_mask:0xf bank_mask:0xf bound_ctrl:1
	s_waitcnt lgkmcnt(9)
	v_pk_fma_f32 v[114:115], v[48:49], v[56:57], v[114:115] op_sel:[0,1,0] op_sel_hi:[1,1,1]
	ds_read_b128 v[92:95], v6 offset:26880
	v_pk_fma_f32 v[116:117], v[50:51], v[56:57], v[116:117] op_sel:[0,1,0] op_sel_hi:[1,1,1]
	v_pk_fma_f32 v[114:115], v[44:45], v[10:11], v[114:115] op_sel_hi:[1,0,1] neg_lo:[1,0,0] neg_hi:[1,0,0]
	ds_read_b128 v[100:103], v6 offset:27392
	v_pk_fma_f32 v[116:117], v[46:47], v[10:11], v[116:117] op_sel_hi:[1,0,1] neg_lo:[1,0,0] neg_hi:[1,0,0]
	v_pk_fma_f32 v[2:3], v[52:53], v[10:11], v[114:115] op_sel:[0,1,0] op_sel_hi:[1,1,1] neg_lo:[1,0,0] neg_hi:[1,0,0]
	v_pk_fma_f32 v[4:5], v[54:55], v[10:11], v[116:117] op_sel:[0,1,0] op_sel_hi:[1,1,1] neg_lo:[1,0,0] neg_hi:[1,0,0]
	ds_write2st64_b32 v9, v14, v15 offset0:80 offset1:84
	s_waitcnt lgkmcnt(4)
	v_pk_mul_f32 v[10:11], v[2:3], v[68:69] op_sel_hi:[0,1]
	ds_read_b128 v[20:23], v6 offset:27648
	v_pk_fma_f32 v[14:15], v[2:3], v[72:73], v[106:107] op_sel_hi:[0,1,1]
	v_pk_fma_f32 v[10:11], v[2:3], v[70:71], v[10:11] op_sel:[1,0,0] op_sel_hi:[1,1,1]
	ds_read_b128 v[24:27], v6 offset:27904
	v_pk_fma_f32 v[14:15], v[2:3], v[74:75], v[14:15] op_sel:[1,0,0] op_sel_hi:[1,1,1]
	v_pk_fma_f32 v[10:11], v[4:5], v[76:77], v[10:11] op_sel_hi:[0,1,1]
	v_pk_fma_f32 v[14:15], v[4:5], v[80:81], v[14:15] op_sel_hi:[0,1,1]
	ds_read_b128 v[56:59], v7 offset:3072
	v_pk_fma_f32 v[10:11], v[4:5], v[78:79], v[10:11] op_sel:[1,0,0] op_sel_hi:[1,1,1]
	v_pk_mul_f32 v[114:115], v[2:3], v[84:85]
	ds_read_b128 v[28:31], v6 offset:28160
	v_pk_mul_f32 v[116:117], v[4:5], v[86:87]
	v_add_f32_dpp v10, v10, v10 row_ror:8 row_mask:0xf bank_mask:0xf bound_ctrl:1
	v_add_f32_dpp v11, v11, v11 row_ror:8 row_mask:0xf bank_mask:0xf bound_ctrl:1
	ds_read_b128 v[32:35], v6 offset:28416
	v_pk_fma_f32 v[14:15], v[4:5], v[82:83], v[14:15] op_sel:[1,0,0] op_sel_hi:[1,1,1]
	v_add_f32_dpp v10, v10, v10 row_ror:4 row_mask:0xf bank_mask:0xf bound_ctrl:1
	ds_read_b128 v[36:39], v6 offset:28672
	v_add_f32_dpp v11, v11, v11 row_ror:4 row_mask:0xf bank_mask:0xf bound_ctrl:1
	v_pk_fma_f32 v[114:115], v[88:89], v[104:105], v[114:115] op_sel_hi:[1,0,1]
	v_add_f32_dpp v10, v10, v10 row_ror:2 row_mask:0xf bank_mask:0xf bound_ctrl:1
	ds_read_b128 v[40:43], v6 offset:28928
	v_add_f32_dpp v11, v11, v11 row_ror:2 row_mask:0xf bank_mask:0xf bound_ctrl:1
	v_pk_fma_f32 v[116:117], v[90:91], v[104:105], v[116:117] op_sel_hi:[1,0,1]
	ds_read_b128 v[48:51], v6 offset:29440
	v_add_f32_dpp v10, v10, v10 row_ror:1 row_mask:0xf bank_mask:0xf bound_ctrl:1
	v_add_f32_dpp v11, v11, v11 row_ror:1 row_mask:0xf bank_mask:0xf bound_ctrl:1
	s_waitcnt lgkmcnt(9)
	v_pk_fma_f32 v[114:115], v[96:97], v[104:105], v[114:115] op_sel:[0,1,0] op_sel_hi:[1,1,1]
	ds_read_b128 v[44:47], v6 offset:29184
	v_pk_fma_f32 v[116:117], v[98:99], v[104:105], v[116:117] op_sel:[0,1,0] op_sel_hi:[1,1,1]
	v_pk_fma_f32 v[114:115], v[92:93], v[10:11], v[114:115] op_sel_hi:[1,0,1] neg_lo:[1,0,0] neg_hi:[1,0,0]
	ds_read_b128 v[52:55], v6 offset:29696
	v_pk_fma_f32 v[116:117], v[94:95], v[10:11], v[116:117] op_sel_hi:[1,0,1] neg_lo:[1,0,0] neg_hi:[1,0,0]
	v_pk_fma_f32 v[2:3], v[100:101], v[10:11], v[114:115] op_sel:[0,1,0] op_sel_hi:[1,1,1] neg_lo:[1,0,0] neg_hi:[1,0,0]
	v_pk_fma_f32 v[4:5], v[102:103], v[10:11], v[116:117] op_sel:[0,1,0] op_sel_hi:[1,1,1] neg_lo:[1,0,0] neg_hi:[1,0,0]
	ds_write2st64_b32 v9, v14, v15 offset0:88 offset1:92
	s_waitcnt lgkmcnt(4)
	v_pk_mul_f32 v[10:11], v[2:3], v[20:21] op_sel_hi:[0,1]
	ds_read_b128 v[68:71], v6 offset:29952
	v_pk_fma_f32 v[14:15], v[2:3], v[24:25], v[58:59] op_sel_hi:[0,1,1]
	v_pk_fma_f32 v[10:11], v[2:3], v[22:23], v[10:11] op_sel:[1,0,0] op_sel_hi:[1,1,1]
	ds_read_b128 v[72:75], v6 offset:30208
	v_pk_fma_f32 v[14:15], v[2:3], v[26:27], v[14:15] op_sel:[1,0,0] op_sel_hi:[1,1,1]
	v_pk_fma_f32 v[10:11], v[4:5], v[28:29], v[10:11] op_sel_hi:[0,1,1]
	v_pk_fma_f32 v[14:15], v[4:5], v[32:33], v[14:15] op_sel_hi:[0,1,1]
	ds_read_b128 v[104:107], v7 offset:3328
	v_pk_fma_f32 v[10:11], v[4:5], v[30:31], v[10:11] op_sel:[1,0,0] op_sel_hi:[1,1,1]
	v_pk_mul_f32 v[114:115], v[2:3], v[36:37]
	ds_read_b128 v[76:79], v6 offset:30464
	v_pk_mul_f32 v[116:117], v[4:5], v[38:39]
	v_add_f32_dpp v10, v10, v10 row_ror:8 row_mask:0xf bank_mask:0xf bound_ctrl:1
	v_add_f32_dpp v11, v11, v11 row_ror:8 row_mask:0xf bank_mask:0xf bound_ctrl:1
	ds_read_b128 v[80:83], v6 offset:30720
	v_pk_fma_f32 v[14:15], v[4:5], v[34:35], v[14:15] op_sel:[1,0,0] op_sel_hi:[1,1,1]
	v_add_f32_dpp v10, v10, v10 row_ror:4 row_mask:0xf bank_mask:0xf bound_ctrl:1
	ds_read_b128 v[84:87], v6 offset:30976
	v_add_f32_dpp v11, v11, v11 row_ror:4 row_mask:0xf bank_mask:0xf bound_ctrl:1
	v_pk_fma_f32 v[114:115], v[40:41], v[56:57], v[114:115] op_sel_hi:[1,0,1]
	v_add_f32_dpp v10, v10, v10 row_ror:2 row_mask:0xf bank_mask:0xf bound_ctrl:1
	ds_read_b128 v[88:91], v6 offset:31232
	v_add_f32_dpp v11, v11, v11 row_ror:2 row_mask:0xf bank_mask:0xf bound_ctrl:1
	v_pk_fma_f32 v[116:117], v[42:43], v[56:57], v[116:117] op_sel_hi:[1,0,1]
	ds_read_b128 v[96:99], v6 offset:31744
	v_add_f32_dpp v10, v10, v10 row_ror:1 row_mask:0xf bank_mask:0xf bound_ctrl:1
	v_add_f32_dpp v11, v11, v11 row_ror:1 row_mask:0xf bank_mask:0xf bound_ctrl:1
	s_waitcnt lgkmcnt(9)
	v_pk_fma_f32 v[114:115], v[48:49], v[56:57], v[114:115] op_sel:[0,1,0] op_sel_hi:[1,1,1]
	ds_read_b128 v[92:95], v6 offset:31488
	v_pk_fma_f32 v[116:117], v[50:51], v[56:57], v[116:117] op_sel:[0,1,0] op_sel_hi:[1,1,1]
	v_pk_fma_f32 v[114:115], v[44:45], v[10:11], v[114:115] op_sel_hi:[1,0,1] neg_lo:[1,0,0] neg_hi:[1,0,0]
	ds_read_b128 v[100:103], v6 offset:32000
	v_pk_fma_f32 v[116:117], v[46:47], v[10:11], v[116:117] op_sel_hi:[1,0,1] neg_lo:[1,0,0] neg_hi:[1,0,0]
	v_pk_fma_f32 v[2:3], v[52:53], v[10:11], v[114:115] op_sel:[0,1,0] op_sel_hi:[1,1,1] neg_lo:[1,0,0] neg_hi:[1,0,0]
	v_pk_fma_f32 v[4:5], v[54:55], v[10:11], v[116:117] op_sel:[0,1,0] op_sel_hi:[1,1,1] neg_lo:[1,0,0] neg_hi:[1,0,0]
	ds_write2st64_b32 v9, v14, v15 offset0:96 offset1:100
	s_waitcnt lgkmcnt(4)
	v_pk_mul_f32 v[10:11], v[2:3], v[68:69] op_sel_hi:[0,1]
	ds_read_b128 v[20:23], v6 offset:32256
	v_pk_fma_f32 v[14:15], v[2:3], v[72:73], v[106:107] op_sel_hi:[0,1,1]
	v_pk_fma_f32 v[10:11], v[2:3], v[70:71], v[10:11] op_sel:[1,0,0] op_sel_hi:[1,1,1]
	ds_read_b128 v[24:27], v6 offset:32512
	v_pk_fma_f32 v[14:15], v[2:3], v[74:75], v[14:15] op_sel:[1,0,0] op_sel_hi:[1,1,1]
	v_pk_fma_f32 v[10:11], v[4:5], v[76:77], v[10:11] op_sel_hi:[0,1,1]
	v_pk_fma_f32 v[14:15], v[4:5], v[80:81], v[14:15] op_sel_hi:[0,1,1]
	ds_read_b128 v[56:59], v7 offset:3584
	v_pk_fma_f32 v[10:11], v[4:5], v[78:79], v[10:11] op_sel:[1,0,0] op_sel_hi:[1,1,1]
	v_pk_mul_f32 v[114:115], v[2:3], v[84:85]
	ds_read_b128 v[28:31], v6 offset:32768
	v_pk_mul_f32 v[116:117], v[4:5], v[86:87]
	v_add_f32_dpp v10, v10, v10 row_ror:8 row_mask:0xf bank_mask:0xf bound_ctrl:1
	v_add_f32_dpp v11, v11, v11 row_ror:8 row_mask:0xf bank_mask:0xf bound_ctrl:1
	ds_read_b128 v[32:35], v6 offset:33024
	v_pk_fma_f32 v[14:15], v[4:5], v[82:83], v[14:15] op_sel:[1,0,0] op_sel_hi:[1,1,1]
	v_add_f32_dpp v10, v10, v10 row_ror:4 row_mask:0xf bank_mask:0xf bound_ctrl:1
	ds_read_b128 v[36:39], v6 offset:33280
	v_add_f32_dpp v11, v11, v11 row_ror:4 row_mask:0xf bank_mask:0xf bound_ctrl:1
	v_pk_fma_f32 v[114:115], v[88:89], v[104:105], v[114:115] op_sel_hi:[1,0,1]
	v_add_f32_dpp v10, v10, v10 row_ror:2 row_mask:0xf bank_mask:0xf bound_ctrl:1
	ds_read_b128 v[40:43], v6 offset:33536
	v_add_f32_dpp v11, v11, v11 row_ror:2 row_mask:0xf bank_mask:0xf bound_ctrl:1
	v_pk_fma_f32 v[116:117], v[90:91], v[104:105], v[116:117] op_sel_hi:[1,0,1]
	ds_read_b128 v[48:51], v6 offset:34048
	v_add_f32_dpp v10, v10, v10 row_ror:1 row_mask:0xf bank_mask:0xf bound_ctrl:1
	v_add_f32_dpp v11, v11, v11 row_ror:1 row_mask:0xf bank_mask:0xf bound_ctrl:1
	s_waitcnt lgkmcnt(9)
	v_pk_fma_f32 v[114:115], v[96:97], v[104:105], v[114:115] op_sel:[0,1,0] op_sel_hi:[1,1,1]
	ds_read_b128 v[44:47], v6 offset:33792
	v_pk_fma_f32 v[116:117], v[98:99], v[104:105], v[116:117] op_sel:[0,1,0] op_sel_hi:[1,1,1]
	v_pk_fma_f32 v[114:115], v[92:93], v[10:11], v[114:115] op_sel_hi:[1,0,1] neg_lo:[1,0,0] neg_hi:[1,0,0]
	ds_read_b128 v[52:55], v6 offset:34304
	v_pk_fma_f32 v[116:117], v[94:95], v[10:11], v[116:117] op_sel_hi:[1,0,1] neg_lo:[1,0,0] neg_hi:[1,0,0]
	v_pk_fma_f32 v[2:3], v[100:101], v[10:11], v[114:115] op_sel:[0,1,0] op_sel_hi:[1,1,1] neg_lo:[1,0,0] neg_hi:[1,0,0]
	v_pk_fma_f32 v[4:5], v[102:103], v[10:11], v[116:117] op_sel:[0,1,0] op_sel_hi:[1,1,1] neg_lo:[1,0,0] neg_hi:[1,0,0]
	ds_write2st64_b32 v9, v14, v15 offset0:104 offset1:108
	s_waitcnt lgkmcnt(4)
	v_pk_mul_f32 v[10:11], v[2:3], v[20:21] op_sel_hi:[0,1]
	ds_read_b128 v[68:71], v6 offset:34560
	v_pk_fma_f32 v[14:15], v[2:3], v[24:25], v[58:59] op_sel_hi:[0,1,1]
	v_pk_fma_f32 v[10:11], v[2:3], v[22:23], v[10:11] op_sel:[1,0,0] op_sel_hi:[1,1,1]
	ds_read_b128 v[72:75], v6 offset:34816
	v_pk_fma_f32 v[14:15], v[2:3], v[26:27], v[14:15] op_sel:[1,0,0] op_sel_hi:[1,1,1]
	v_pk_fma_f32 v[10:11], v[4:5], v[28:29], v[10:11] op_sel_hi:[0,1,1]
	v_pk_fma_f32 v[14:15], v[4:5], v[32:33], v[14:15] op_sel_hi:[0,1,1]
	ds_read_b128 v[104:107], v7 offset:3840
	v_pk_fma_f32 v[10:11], v[4:5], v[30:31], v[10:11] op_sel:[1,0,0] op_sel_hi:[1,1,1]
	v_pk_mul_f32 v[114:115], v[2:3], v[36:37]
	ds_read_b128 v[76:79], v6 offset:35072
	v_pk_mul_f32 v[116:117], v[4:5], v[38:39]
	v_add_f32_dpp v10, v10, v10 row_ror:8 row_mask:0xf bank_mask:0xf bound_ctrl:1
	v_add_f32_dpp v11, v11, v11 row_ror:8 row_mask:0xf bank_mask:0xf bound_ctrl:1
	ds_read_b128 v[80:83], v6 offset:35328
	v_pk_fma_f32 v[14:15], v[4:5], v[34:35], v[14:15] op_sel:[1,0,0] op_sel_hi:[1,1,1]
	v_add_f32_dpp v10, v10, v10 row_ror:4 row_mask:0xf bank_mask:0xf bound_ctrl:1
	ds_read_b128 v[84:87], v6 offset:35584
	v_add_f32_dpp v11, v11, v11 row_ror:4 row_mask:0xf bank_mask:0xf bound_ctrl:1
	v_pk_fma_f32 v[114:115], v[40:41], v[56:57], v[114:115] op_sel_hi:[1,0,1]
	v_add_f32_dpp v10, v10, v10 row_ror:2 row_mask:0xf bank_mask:0xf bound_ctrl:1
	ds_read_b128 v[88:91], v6 offset:35840
	v_add_f32_dpp v11, v11, v11 row_ror:2 row_mask:0xf bank_mask:0xf bound_ctrl:1
	v_pk_fma_f32 v[116:117], v[42:43], v[56:57], v[116:117] op_sel_hi:[1,0,1]
	ds_read_b128 v[96:99], v6 offset:36352
	v_add_f32_dpp v10, v10, v10 row_ror:1 row_mask:0xf bank_mask:0xf bound_ctrl:1
	v_add_f32_dpp v11, v11, v11 row_ror:1 row_mask:0xf bank_mask:0xf bound_ctrl:1
	s_waitcnt lgkmcnt(9)
	v_pk_fma_f32 v[114:115], v[48:49], v[56:57], v[114:115] op_sel:[0,1,0] op_sel_hi:[1,1,1]
	ds_read_b128 v[92:95], v6 offset:36096
	v_pk_fma_f32 v[116:117], v[50:51], v[56:57], v[116:117] op_sel:[0,1,0] op_sel_hi:[1,1,1]
	v_pk_fma_f32 v[114:115], v[44:45], v[10:11], v[114:115] op_sel_hi:[1,0,1] neg_lo:[1,0,0] neg_hi:[1,0,0]
	ds_read_b128 v[100:103], v6 offset:36608
	v_pk_fma_f32 v[116:117], v[46:47], v[10:11], v[116:117] op_sel_hi:[1,0,1] neg_lo:[1,0,0] neg_hi:[1,0,0]
	v_pk_fma_f32 v[2:3], v[52:53], v[10:11], v[114:115] op_sel:[0,1,0] op_sel_hi:[1,1,1] neg_lo:[1,0,0] neg_hi:[1,0,0]
	v_pk_fma_f32 v[4:5], v[54:55], v[10:11], v[116:117] op_sel:[0,1,0] op_sel_hi:[1,1,1] neg_lo:[1,0,0] neg_hi:[1,0,0]
	ds_write2st64_b32 v9, v14, v15 offset0:112 offset1:116
	s_waitcnt lgkmcnt(4)
	v_pk_mul_f32 v[10:11], v[2:3], v[68:69] op_sel_hi:[0,1]
	v_pk_fma_f32 v[14:15], v[2:3], v[72:73], v[106:107] op_sel_hi:[0,1,1]
	v_pk_fma_f32 v[10:11], v[2:3], v[70:71], v[10:11] op_sel:[1,0,0] op_sel_hi:[1,1,1]
	v_pk_fma_f32 v[14:15], v[2:3], v[74:75], v[14:15] op_sel:[1,0,0] op_sel_hi:[1,1,1]
	v_pk_fma_f32 v[10:11], v[4:5], v[76:77], v[10:11] op_sel_hi:[0,1,1]
	v_pk_fma_f32 v[14:15], v[4:5], v[80:81], v[14:15] op_sel_hi:[0,1,1]
	v_pk_fma_f32 v[10:11], v[4:5], v[78:79], v[10:11] op_sel:[1,0,0] op_sel_hi:[1,1,1]
	v_pk_mul_f32 v[114:115], v[2:3], v[84:85]
	v_pk_mul_f32 v[116:117], v[4:5], v[86:87]
	v_add_f32_dpp v10, v10, v10 row_ror:8 row_mask:0xf bank_mask:0xf bound_ctrl:1
	v_add_f32_dpp v11, v11, v11 row_ror:8 row_mask:0xf bank_mask:0xf bound_ctrl:1
	v_pk_fma_f32 v[14:15], v[4:5], v[82:83], v[14:15] op_sel:[1,0,0] op_sel_hi:[1,1,1]
	v_add_f32_dpp v10, v10, v10 row_ror:4 row_mask:0xf bank_mask:0xf bound_ctrl:1
	v_add_f32_dpp v11, v11, v11 row_ror:4 row_mask:0xf bank_mask:0xf bound_ctrl:1
	v_pk_fma_f32 v[114:115], v[88:89], v[104:105], v[114:115] op_sel_hi:[1,0,1]
	v_add_f32_dpp v10, v10, v10 row_ror:2 row_mask:0xf bank_mask:0xf bound_ctrl:1
	v_add_f32_dpp v11, v11, v11 row_ror:2 row_mask:0xf bank_mask:0xf bound_ctrl:1
	v_pk_fma_f32 v[116:117], v[90:91], v[104:105], v[116:117] op_sel_hi:[1,0,1]
	v_add_f32_dpp v10, v10, v10 row_ror:1 row_mask:0xf bank_mask:0xf bound_ctrl:1
	v_add_f32_dpp v11, v11, v11 row_ror:1 row_mask:0xf bank_mask:0xf bound_ctrl:1
	s_waitcnt lgkmcnt(1)
	v_pk_fma_f32 v[114:115], v[96:97], v[104:105], v[114:115] op_sel:[0,1,0] op_sel_hi:[1,1,1]
	v_pk_fma_f32 v[116:117], v[98:99], v[104:105], v[116:117] op_sel:[0,1,0] op_sel_hi:[1,1,1]
	v_pk_fma_f32 v[114:115], v[92:93], v[10:11], v[114:115] op_sel_hi:[1,0,1] neg_lo:[1,0,0] neg_hi:[1,0,0]
	v_pk_fma_f32 v[116:117], v[94:95], v[10:11], v[116:117] op_sel_hi:[1,0,1] neg_lo:[1,0,0] neg_hi:[1,0,0]
	v_pk_fma_f32 v[2:3], v[100:101], v[10:11], v[114:115] op_sel:[0,1,0] op_sel_hi:[1,1,1] neg_lo:[1,0,0] neg_hi:[1,0,0]
	v_pk_fma_f32 v[4:5], v[102:103], v[10:11], v[116:117] op_sel:[0,1,0] op_sel_hi:[1,1,1] neg_lo:[1,0,0] neg_hi:[1,0,0]
	ds_write2st64_b32 v9, v14, v15 offset0:120 offset1:124
	v_add_u32_e32 v6, s1, v6
	v_add_u32_e32 v7, vcc_lo, v7
	v_add_u32_e32 v9, s1, v9
	s_sub_i32 s1, 0, s1
	s_sub_i32 vcc_lo, 0, vcc_lo
	s_add_i32 s0, s0, 1
	s_cmpk_eq_i32 s0, 0x200
	s_waitcnt lgkmcnt(0)
	s_barrier
	s_cbranch_scc0 .LBB0_652
	s_mov_b64 s[0:1], 0
